# nt policy on the S5 u-slice loads (non-final and final passes), on top of the resid nt version
# speedup vs baseline: 1.0125x; 1.0004x over previous
.LBB0_782:
	v_mul_hi_i32 v0, v125, s22
	v_lshrrev_b32_e32 v2, 31, v0
	v_ashrrev_i32_e32 v0, 5, v0
	v_add_u32_e32 v0, v0, v2
	v_mul_lo_u32 v2, v0, s23
	v_sub_u32_e32 v50, v125, v2
	v_ashrrev_i32_e32 v132, 6, v0
	v_mov_b32_e32 v36, v189
	v_mov_b32_e32 v34, v189
	s_mov_b32 s0, s33
	v_cmp_lt_i32_e64 s[6:7], s24, v50
	v_cmp_gt_i32_e32 vcc, s25, v50
	v_lshlrev_b32_e32 v2, 6, v50
	v_ashrrev_i32_e32 v133, 31, v132
	s_and_saveexec_b64 s[0:1], vcc
	s_xor_b64 s[0:1], exec, s[0:1]
	v_lshlrev_b64 v[8:9], 13, v[132:133]
	v_ashrrev_i32_e32 v3, 31, v2
	v_lshl_add_u64 v[120:121], v[8:9], 0, v[2:3]
	s_andn2_saveexec_b64 s[0:1], s[0:1]
	v_lshlrev_b32_e32 v3, 8, v132
	v_add3_u32 v120, v2, v3, s26
	v_ashrrev_i32_e32 v121, 31, v120
	s_or_b64 exec, exec, s[0:1]
	global_load_dwordx2 v[48:49], v1, s[14:15] offset:48
	global_load_dwordx4 v[44:47], v1, s[14:15] offset:32
	global_load_dwordx4 v[8:11], v1, s[14:15] offset:16
	global_load_dwordx4 v[12:15], v1, s[14:15]
	v_and_b32_e32 v124, 63, v0
	v_and_b32_e32 v122, 15, v34
	v_mov_b32_e32 v123, v1
	v_lshlrev_b32_e32 v0, 5, v124
	v_lshl_add_u64 v[2:3], v[120:121], 0, v[122:123]
	v_lshl_add_u64 v[16:17], s[60:61], 0, v[0:1]
	v_and_b32_e32 v0, 48, v34
	v_and_b32_e32 v131, 63, v34
	v_lshl_add_u64 v[18:19], v[16:17], 0, v[0:1]
	v_mov_b32_e32 v16, 0
	v_lshlrev_b64 v[2:3], 13, v[2:3]
	v_cmp_lt_u32_e64 s[2:3], 31, v131
	v_cmp_gt_u32_e64 s[0:1], 32, v131
	v_lshl_add_u64 v[32:33], v[18:19], 0, v[2:3]
	v_mov_b32_e32 v17, v16
	v_mov_b32_e32 v18, v16
	v_mov_b32_e32 v19, v16
	s_and_saveexec_b64 s[10:11], s[0:1]
	s_cbranch_execz .LBB0_788
	global_load_dwordx4 v[16:19], v[32:33], off nt
.LBB0_788:
	s_or_b64 exec, exec, s[10:11]
	v_mov_b32_e32 v2, v1
	v_mov_b32_e32 v3, v1
	v_mov_b32_e32 v0, v1
	v_mov_b64_e32 v[22:23], v[2:3]
	v_mov_b64_e32 v[20:21], v[0:1]
	s_and_saveexec_b64 s[10:11], s[0:1]
	s_cbranch_execz .LBB0_790
	v_add_co_u32_e32 v20, vcc, 0x20000, v32
	s_nop 1
	v_addc_co_u32_e32 v21, vcc, 0, v33, vcc
	global_load_dwordx4 v[20:23], v[20:21], off nt
.LBB0_790:
	s_or_b64 exec, exec, s[10:11]
	v_mov_b64_e32 v[26:27], v[2:3]
	v_mov_b64_e32 v[24:25], v[0:1]
	s_and_saveexec_b64 s[10:11], s[0:1]
	s_cbranch_execz .LBB0_792
	v_add_co_u32_e32 v2, vcc, 0x40000, v32
	s_nop 1
	v_addc_co_u32_e32 v3, vcc, 0, v33, vcc
	global_load_dwordx4 v[24:27], v[2:3], off nt
.LBB0_792:
	s_or_b64 exec, exec, s[10:11]
	v_mov_b32_e32 v0, 0
	v_mov_b32_e32 v28, 0
	v_mov_b32_e32 v29, 0
	v_mov_b32_e32 v30, 0
	v_mov_b32_e32 v31, 0
	s_and_saveexec_b64 s[10:11], s[0:1]
	s_cbranch_execz .LBB0_794
	v_add_co_u32_e32 v2, vcc, 0x60000, v32
	s_nop 1
	v_addc_co_u32_e32 v3, vcc, 0, v33, vcc
	global_load_dwordx4 v[28:31], v[2:3], off nt
